# phase-6 setup c_re/c_im loads batched; qknorm V tile loads batched
# speedup vs baseline: 1.0155x; 1.0001x over previous
.LBB0_93:
	s_or_b64 exec, exec, s[6:7]
	v_mul_f32_e32 v4, v4, v0
	v_mul_f32_e32 v7, 0x3fb8aa3b, v4
	s_mov_b32 s0, 0x3fb8aa3b
	v_fma_f32 v10, v4, s0, -v7
	v_rndne_f32_e32 v11, v7
	v_fmac_f32_e32 v10, 0x32a5705f, v4
	v_sub_f32_e32 v7, v7, v11
	v_add_f32_e32 v7, v7, v10
	v_lshlrev_b32_e32 v10, 6, v25
	s_movk_i32 s0, 0x800
	v_or3_b32 v23, v10, v34, s0
	v_cvt_i32_f32_e32 v22, v11
	global_load_dwordx4 v[10:13], v23, s[12:13] offset:16
	global_load_dwordx4 v[14:17], v23, s[12:13]
	global_load_dwordx4 v[18:21], v23, s[22:23] offset:16
	global_load_dwordx4 v[34:37], v23, s[22:23]
	v_exp_f32_e32 v7, v7
	s_mov_b32 s0, 0xc2ce8ed0
	v_cmp_ngt_f32_e32 vcc, s0, v4
	s_mov_b32 s0, 0x42b17218
	v_ldexp_f32 v7, v7, v22
	v_cndmask_b32_e32 v7, 0, v7, vcc
	v_cmp_nlt_f32_e32 vcc, s0, v4
	s_movk_i32 s0, 0x1f8
	v_ashrrev_i32_e32 v165, 6, v28
	v_cndmask_b32_e32 v4, v198, v7, vcc
	v_mul_f32_e32 v7, v6, v6
	v_fmamk_f32 v22, v7, 0xb94c1982, v194
	v_fmaak_f32 v22, v7, v22, 0xbe2aaa9d
	v_mul_f32_e32 v22, v7, v22
	v_fmac_f32_e32 v6, v6, v22
	v_fmamk_f32 v22, v7, 0x37d75334, v195
	v_fmaak_f32 v22, v7, v22, 0x3d2aabf7
	v_fmaak_f32 v22, v7, v22, 0xbf000004
	v_fma_f32 v7, v7, v22, 1.0
	v_and_b32_e32 v22, 1, v5
	v_cmp_eq_u32_e32 vcc, 0, v22
	v_lshlrev_b32_e32 v5, 30, v5
	s_nop 0
	v_cndmask_b32_e64 v6, -v6, v7, vcc
	v_bitop3_b32 v5, v5, v6, s35 bitop3:0x6c
	v_mul_f32_e32 v6, v9, v9
	v_fmamk_f32 v7, v6, 0xb94c1982, v194
	v_fmaak_f32 v7, v6, v7, 0xbe2aaa9d
	v_mul_f32_e32 v7, v6, v7
	v_fmac_f32_e32 v9, v9, v7
	v_fmamk_f32 v7, v6, 0x37d75334, v195
	v_fmaak_f32 v7, v6, v7, 0x3d2aabf7
	v_fmaak_f32 v7, v6, v7, 0xbf000004
	v_fma_f32 v6, v6, v7, 1.0
	v_and_b32_e32 v7, 1, v8
	v_cmp_eq_u32_e64 s[6:7], 0, v7
	v_lshlrev_b32_e32 v7, 30, v8
	v_cmp_class_f32_e64 vcc, v2, s0
	v_and_b32_e32 v7, 0x80000000, v7
	v_xor_b32_e32 v2, v3, v2
	v_cndmask_b32_e64 v6, v6, v9, s[6:7]
	v_xor_b32_e32 v2, v2, v7
	v_xor_b32_e32 v2, v2, v6
	v_cndmask_b32_e32 v2, v201, v2, vcc
	v_cndmask_b32_e32 v5, v201, v5, vcc
	v_mul_f32_e32 v114, v4, v2
	v_mul_f32_e32 v2, v1, v1
	v_fma_f32 v3, v4, v5, -1.0
	v_mul_f32_e32 v6, v1, v114
	v_fmac_f32_e32 v2, v0, v0
	v_fmac_f32_e32 v6, v0, v3
	v_div_scale_f32 v7, s[6:7], v2, v2, v6
	v_rcp_f32_e32 v8, v7
	v_mul_f32_e32 v1, v1, v3
	v_fma_f32 v0, v0, v114, -v1
	v_div_scale_f32 v1, s[6:7], v2, v2, v0
	v_fma_f32 v22, -v7, v8, 1.0
	v_fmac_f32_e32 v8, v22, v8
	v_div_scale_f32 v22, vcc, v6, v2, v6
	v_mul_f32_e32 v23, v22, v8
	v_fma_f32 v38, -v7, v23, v22
	v_rcp_f32_e32 v3, v1
	v_fmac_f32_e32 v23, v38, v8
	v_fma_f32 v7, -v7, v23, v22
	v_div_fmas_f32 v7, v7, v8, v23
	v_div_fixup_f32 v6, v7, v2, v6
	v_fma_f32 v7, -v1, v3, 1.0
	v_fmac_f32_e32 v3, v7, v3
	v_div_scale_f32 v7, vcc, v0, v2, v0
	v_mul_f32_e32 v8, v7, v3
	v_fma_f32 v22, -v1, v8, v7
	v_fmac_f32_e32 v8, v22, v3
	v_fma_f32 v1, -v1, v8, v7
	v_div_fmas_f32 v1, v1, v3, v8
	v_div_fixup_f32 v0, v1, v2, v0
	s_waitcnt vmcnt(2)
	v_mul_f32_e32 v1, v14, v0
	s_waitcnt vmcnt(0)
	v_fma_f32 v1, v34, v6, -v1
	v_mul_f32_e32 v2, v15, v0
	v_fma_f32 v2, v35, v6, -v2
	v_cvt_pk_bf16_f32 v72, v1, v2
	v_mul_f32_e32 v1, v16, v0
	v_fma_f32 v1, v36, v6, -v1
	v_mul_f32_e32 v2, v17, v0
	v_fma_f32 v2, v37, v6, -v2
	v_cvt_pk_bf16_f32 v73, v1, v2
	v_mul_f32_e32 v1, v10, v0
	v_fma_f32 v1, v18, v6, -v1
	v_mul_f32_e32 v2, v11, v0
	v_fma_f32 v2, v19, v6, -v2
	v_cvt_pk_bf16_f32 v74, v1, v2
	v_mul_f32_e32 v1, v12, v0
	v_fma_f32 v1, v20, v6, -v1
	v_mul_f32_e32 v2, v13, v0
	v_fma_f32 v2, v21, v6, -v2
	v_cvt_pk_bf16_f32 v75, v1, v2
	v_mul_f32_e32 v1, v34, v0
	v_fmac_f32_e32 v1, v14, v6
	v_mul_f32_e32 v2, v35, v0
	v_fmac_f32_e32 v2, v15, v6
	v_cvt_pk_bf16_f32 v76, v1, v2
	v_mul_f32_e32 v1, v36, v0
	v_fmac_f32_e32 v1, v16, v6
	v_mul_f32_e32 v2, v37, v0
	v_fmac_f32_e32 v2, v17, v6
	v_cvt_pk_bf16_f32 v77, v1, v2
	v_mul_f32_e32 v1, v18, v0
	v_fmac_f32_e32 v1, v10, v6
	v_mul_f32_e32 v2, v19, v0
	v_fmac_f32_e32 v2, v11, v6
	v_cvt_pk_bf16_f32 v78, v1, v2
	v_mul_f32_e32 v1, v20, v0
	v_mul_f32_e32 v0, v21, v0
	v_fmac_f32_e32 v1, v12, v6
	v_fmac_f32_e32 v0, v13, v6
	v_cvt_pk_bf16_f32 v79, v1, v0
	s_load_dwordx4 s[8:11], s[92:93], 0x60
	v_and_b32_e32 v0, 15, v24
	v_lshlrev_b32_e32 v1, 4, v29
	v_and_b32_e32 v9, 63, v24
	v_or_b32_e32 v3, v1, v0
	v_lshrrev_b32_e32 v2, 4, v9
	v_lshlrev_b32_e32 v158, 8, v3
	s_waitcnt lgkmcnt(0)
	v_lshl_add_u64 v[6:7], s[8:9], 0, v[158:159]
	v_lshl_add_u64 v[8:9], s[10:11], 0, v[158:159]
	v_lshlrev_b32_e32 v158, 3, v2
	v_lshl_add_u64 v[6:7], v[6:7], 0, v[158:159]
	v_lshl_add_u64 v[8:9], v[8:9], 0, v[158:159]
	s_movk_i32 s0, 0x80
	v_cmp_gt_i32_e32 vcc, s0, v165
	global_load_dword v214, v[6:7], off
	global_load_dword v215, v[6:7], off offset:128
	global_load_dword v216, v[8:9], off
	global_load_dword v217, v[8:9], off offset:128
	global_load_dword v218, v[6:7], off offset:4
	global_load_dword v219, v[6:7], off offset:132
	global_load_dword v220, v[8:9], off offset:4
	global_load_dword v221, v[8:9], off offset:132
	global_load_dword v222, v[6:7], off offset:32
	global_load_dword v223, v[6:7], off offset:160
	global_load_dword v224, v[8:9], off offset:32
	global_load_dword v225, v[8:9], off offset:160
	global_load_dword v226, v[6:7], off offset:36
	global_load_dword v227, v[6:7], off offset:164
	global_load_dword v228, v[8:9], off offset:36
	global_load_dword v229, v[8:9], off offset:164
	global_load_dword v230, v[6:7], off offset:64
	global_load_dword v231, v[6:7], off offset:192
	global_load_dword v232, v[8:9], off offset:64
	global_load_dword v233, v[8:9], off offset:192
	global_load_dword v234, v[6:7], off offset:68
	global_load_dword v235, v[6:7], off offset:196
	global_load_dword v236, v[8:9], off offset:68
	global_load_dword v237, v[8:9], off offset:196
	global_load_dword v238, v[6:7], off offset:96
	global_load_dword v239, v[6:7], off offset:224
	global_load_dword v240, v[8:9], off offset:96
	global_load_dword v241, v[8:9], off offset:224
	global_load_dword v242, v[6:7], off offset:100
	global_load_dword v243, v[6:7], off offset:228
	global_load_dword v244, v[8:9], off offset:100
	global_load_dword v245, v[8:9], off offset:228
	s_waitcnt vmcnt(0)
	v_cvt_pk_bf16_f32 v80, v214, v215
	v_xor_b32_e32 v216, 0x80000000, v216
	v_xor_b32_e32 v217, 0x80000000, v217
	v_cvt_pk_bf16_f32 v81, v216, v217
	v_cvt_pk_bf16_f32 v82, v218, v219
	v_xor_b32_e32 v220, 0x80000000, v220
	v_xor_b32_e32 v221, 0x80000000, v221
	v_cvt_pk_bf16_f32 v83, v220, v221
	v_cvt_pk_bf16_f32 v84, v222, v223
	v_xor_b32_e32 v224, 0x80000000, v224
	v_xor_b32_e32 v225, 0x80000000, v225
	v_cvt_pk_bf16_f32 v85, v224, v225
	v_cvt_pk_bf16_f32 v86, v226, v227
	v_xor_b32_e32 v228, 0x80000000, v228
	v_xor_b32_e32 v229, 0x80000000, v229
	v_cvt_pk_bf16_f32 v87, v228, v229
	v_cvt_pk_bf16_f32 v88, v230, v231
	v_xor_b32_e32 v232, 0x80000000, v232
	v_xor_b32_e32 v233, 0x80000000, v233
	v_cvt_pk_bf16_f32 v89, v232, v233
	v_cvt_pk_bf16_f32 v90, v234, v235
	v_xor_b32_e32 v236, 0x80000000, v236
	v_xor_b32_e32 v237, 0x80000000, v237
	v_cvt_pk_bf16_f32 v91, v236, v237
	v_cvt_pk_bf16_f32 v92, v238, v239
	v_xor_b32_e32 v240, 0x80000000, v240
	v_xor_b32_e32 v241, 0x80000000, v241
	v_cvt_pk_bf16_f32 v93, v240, v241
	v_cvt_pk_bf16_f32 v94, v242, v243
	v_xor_b32_e32 v244, 0x80000000, v244
	v_xor_b32_e32 v245, 0x80000000, v245
	v_cvt_pk_bf16_f32 v95, v244, v245
	s_and_saveexec_b64 s[6:7], vcc
	s_cbranch_execz .LBB0_96
	s_load_dwordx2 s[8:9], s[92:93], 0x70
	v_lshlrev_b32_e32 v3, 2, v1
	v_lshl_or_b32 v2, v2, 4, v3
	s_movk_i32 s0, 0x2200
	v_mov_b32_e32 v3, v159
	s_waitcnt lgkmcnt(0)
	global_load_dwordx4 v[96:99], v2, s[8:9]
	v_mul_lo_u32 v2, v27, s0
	v_add_u32_e32 v10, 0, v2
	v_lshlrev_b32_e32 v2, 3, v26
	v_mul_f32_e32 v115, v4, v5
	v_lshl_add_u64 v[2:3], s[90:91], 0, v[2:3]
	v_lshlrev_b32_e32 v4, 3, v25
	v_mov_b32_e32 v5, v159
	v_lshl_add_u64 v[2:3], v[2:3], 0, v[4:5]
	s_mov_b64 s[8:9], 0xbb00000
	v_lshl_add_u64 v[116:117], v[2:3], 0, s[8:9]
	v_lshrrev_b32_e32 v2, 1, v24
	v_and_b32_e32 v5, 12, v2
	v_lshlrev_b32_e32 v2, 1, v1
	v_mov_b32_e32 v3, v159
	v_lshl_add_u64 v[2:3], s[90:91], 0, v[2:3]
	s_mov_b64 s[0:1], 0x7300000
	v_lshl_add_u64 v[6:7], v[2:3], 0, s[0:1]
	v_lshlrev_b32_e32 v8, 1, v33
	v_mov_b32_e32 v9, v159
	v_lshl_add_u64 v[118:119], v[6:7], 0, v[8:9]
	v_lshl_add_u64 v[120:121], v[6:7], 0, v[158:159]
	v_lshl_add_u64 v[2:3], v[2:3], 0, v[158:159]
	s_mov_b64 s[8:9], 0x9300000
	v_lshlrev_b32_e32 v6, 7, v165
	v_add_u32_e32 v1, v10, v4
	v_and_b32_e32 v4, 48, v24
	v_lshl_add_u64 v[122:123], v[2:3], 0, s[8:9]
	v_mul_u32_u24_e32 v3, 0x110, v0
	v_or_b32_e32 v158, v6, v0
	v_lshlrev_b32_e32 v0, 4, v24
	v_mul_f32_e32 v113, v30, v31
	v_and_b32_e32 v11, 3, v24
	v_add_u32_e32 v4, v10, v4
	v_mul_u32_u24_e32 v2, 0x1100, v32
	v_and_or_b32 v0, v0, 64, v6
	v_mov_b32_e32 v124, v113
	v_mov_b32_e32 v125, v112
	v_mov_b32_e32 v126, v115
	v_mov_b32_e32 v127, v114
	v_or3_b32 v174, v0, v5, v11
	v_lshl_or_b32 v128, v165, 1, v32
	s_mov_b32 s10, 0
	s_mov_b64 s[8:9], 0
	v_add_u32_e32 v175, v1, v2
	v_add_u32_e32 v176, v4, v3
	v_add_u32_e32 v190, s10, v174
	v_add_u32_e32 v191, s10, v158
	v_ashrrev_i32_e32 v189, 31, v128
	v_mov_b32_e32 v188, v128
	v_lshlrev_b64 v[188:189], 15, v[188:189]
	v_lshl_add_u64 v[188:189], v[116:117], 0, v[188:189]
	global_load_dwordx2 v[152:153], v[188:189], off
	global_load_dwordx2 v[154:155], v[188:189], off offset:256
	v_mov_b32_e32 v188, v190
	v_ashrrev_i32_e32 v189, 31, v188
	v_lshlrev_b64 v[188:189], 11, v[188:189]
	v_lshl_add_u64 v[188:189], v[118:119], 0, v[188:189]
	global_load_dwordx4 v[100:103], v[188:189], off
	v_add_u32_e32 v188, 16, v190
	v_ashrrev_i32_e32 v189, 31, v188
	v_lshlrev_b64 v[188:189], 11, v[188:189]
	v_lshl_add_u64 v[188:189], v[118:119], 0, v[188:189]
	global_load_dwordx4 v[104:107], v[188:189], off
	v_add_u32_e32 v188, 32, v190
	v_ashrrev_i32_e32 v189, 31, v188
	v_lshlrev_b64 v[188:189], 11, v[188:189]
	v_lshl_add_u64 v[188:189], v[118:119], 0, v[188:189]
	global_load_dwordx4 v[108:111], v[188:189], off
	v_add_u32_e32 v188, 48, v190
	v_ashrrev_i32_e32 v189, 31, v188
	v_lshlrev_b64 v[188:189], 11, v[188:189]
	v_lshl_add_u64 v[188:189], v[118:119], 0, v[188:189]
	global_load_dwordx4 v[132:135], v[188:189], off
	v_mov_b32_e32 v188, v191
	v_ashrrev_i32_e32 v189, 31, v188
	v_lshlrev_b64 v[188:189], 11, v[188:189]
	v_lshl_add_u64 v[188:189], v[120:121], 0, v[188:189]
	global_load_dwordx2 v[136:137], v[188:189], off
	v_add_u32_e32 v188, 64, v191
	v_ashrrev_i32_e32 v189, 31, v188
	v_lshlrev_b64 v[188:189], 11, v[188:189]
	v_lshl_add_u64 v[188:189], v[120:121], 0, v[188:189]
	global_load_dwordx2 v[138:139], v[188:189], off
	v_add_u32_e32 v188, 16, v191
	v_ashrrev_i32_e32 v189, 31, v188
	v_lshlrev_b64 v[188:189], 11, v[188:189]
	v_lshl_add_u64 v[188:189], v[120:121], 0, v[188:189]
	global_load_dwordx2 v[140:141], v[188:189], off
	v_add_u32_e32 v188, 80, v191
	v_ashrrev_i32_e32 v189, 31, v188
	v_lshlrev_b64 v[188:189], 11, v[188:189]
	v_lshl_add_u64 v[188:189], v[120:121], 0, v[188:189]
	global_load_dwordx2 v[142:143], v[188:189], off
	v_add_u32_e32 v188, 32, v191
	v_ashrrev_i32_e32 v189, 31, v188
	v_lshlrev_b64 v[188:189], 11, v[188:189]
	v_lshl_add_u64 v[188:189], v[120:121], 0, v[188:189]
	global_load_dwordx2 v[144:145], v[188:189], off
	v_add_u32_e32 v188, 96, v191
	v_ashrrev_i32_e32 v189, 31, v188
	v_lshlrev_b64 v[188:189], 11, v[188:189]
	v_lshl_add_u64 v[188:189], v[120:121], 0, v[188:189]
	global_load_dwordx2 v[146:147], v[188:189], off
	v_add_u32_e32 v188, 48, v191
	v_ashrrev_i32_e32 v189, 31, v188
	v_lshlrev_b64 v[188:189], 11, v[188:189]
	v_lshl_add_u64 v[188:189], v[120:121], 0, v[188:189]
	global_load_dwordx2 v[148:149], v[188:189], off
	v_add_u32_e32 v188, 112, v191
	v_ashrrev_i32_e32 v189, 31, v188
	v_lshlrev_b64 v[188:189], 11, v[188:189]
	v_lshl_add_u64 v[188:189], v[120:121], 0, v[188:189]
	global_load_dwordx2 v[150:151], v[188:189], off
	s_waitcnt vmcnt(0)

.LBB0_513:
	s_waitcnt vmcnt(9)
	v_lshlrev_b32_e32 v168, 16, v107
	v_and_b32_e32 v169, 0xffff0000, v107
	v_and_b32_e32 v171, 0xffff0000, v106
	v_lshlrev_b32_e32 v170, 16, v106
	v_pk_mul_f32 v[106:107], v[170:171], v[170:171]
	v_pk_mul_f32 v[172:173], v[168:169], v[168:169]
	v_mov_b32_e32 v175, v106
	v_mov_b32_e32 v174, v172
	v_mov_b32_e32 v106, v173
	v_pk_add_f32 v[106:107], v[174:175], v[106:107]
	s_nop 1
	v_mov_b32_dpp v173, v107 quad_perm:[1,0,3,2] row_mask:0xf bank_mask:0xf
	v_mov_b32_dpp v172, v106 quad_perm:[1,0,3,2] row_mask:0xf bank_mask:0xf
	s_mov_b32 s10, 0x358637bd
	v_mov_b32_e32 v176, v60
	v_mov_b32_e32 v177, v62
	v_mov_b32_e32 v62, v61
	s_waitcnt lgkmcnt(0)
	v_pk_add_f32 v[106:107], v[106:107], v[172:173]
	s_nop 1
	v_mov_b32_dpp v173, v107 quad_perm:[2,3,0,1] row_mask:0xf bank_mask:0xf
	v_mov_b32_dpp v172, v106 quad_perm:[2,3,0,1] row_mask:0xf bank_mask:0xf
	s_mov_b32 s2, 0x4c00000
	v_add_u32_e32 v100, 8, v100
	s_waitcnt lgkmcnt(0)
	v_pk_add_f32 v[106:107], v[106:107], v[172:173]
	s_nop 1
	v_mov_b32_dpp v173, v107 row_half_mirror row_mask:0xf bank_mask:0xf
	v_mov_b32_dpp v172, v106 row_half_mirror row_mask:0xf bank_mask:0xf
	s_waitcnt lgkmcnt(0)
	v_pk_add_f32 v[106:107], v[106:107], v[172:173]
	s_nop 1
	v_mov_b32_dpp v173, v107 row_ror:8 row_mask:0xf bank_mask:0xf
	v_mov_b32_dpp v172, v106 row_ror:8 row_mask:0xf bank_mask:0xf
	s_waitcnt lgkmcnt(0)
	v_pk_add_f32 v[106:107], v[106:107], v[172:173]
	s_waitcnt lgkmcnt(0)
	v_mov_b32_e32 v173, v107
	v_mov_b32_e32 v172, v106
	s_nop 1
	v_permlane16_swap_b32_e32 v107, v173
	v_permlane16_swap_b32_e32 v106, v172
	s_nop 0
	v_pk_add_f32 v[106:107], v[106:107], v[172:173]
	s_waitcnt lgkmcnt(0)
	v_mov_b32_e32 v173, v107
	v_mov_b32_e32 v172, v106
	s_nop 1
	v_permlane32_swap_b32_e32 v107, v173
	v_permlane32_swap_b32_e32 v106, v172
	s_nop 0
	v_pk_add_f32 v[172:173], v[106:107], v[172:173]
	v_mov_b64_e32 v[106:107], s[10:11]
	v_pk_fma_f32 v[172:173], v[172:173], s[64:65], v[106:107] op_sel_hi:[1,0,0]
	s_nop 0
	v_mul_f32_e32 v101, 0x4b800000, v173
	v_cmp_gt_f32_e64 s[10:11], s40, v173
	v_cmp_gt_f32_e32 vcc, s40, v172
	s_nop 0
	v_cndmask_b32_e64 v101, v173, v101, s[10:11]
	v_rsq_f32_e32 v101, v101
	s_nop 0
	v_mul_f32_e32 v173, 0x45800000, v101
	v_cndmask_b32_e64 v174, v101, v173, s[10:11]
	v_mul_f32_e32 v101, 0x4b800000, v172
	v_cndmask_b32_e32 v101, v172, v101, vcc
	v_rsq_f32_e32 v101, v101
	v_pk_mul_f32 v[174:175], v[64:65], v[174:175] op_sel_hi:[1,0]
	v_mul_f32_e32 v172, 0x45800000, v101
	v_cndmask_b32_e32 v172, v101, v172, vcc
	v_pk_mul_f32 v[170:171], v[174:175], v[170:171]
	v_pk_mul_f32 v[172:173], v[66:67], v[172:173] op_sel_hi:[1,0]
	v_pk_mul_f32 v[178:179], v[176:177], v[170:171]
	v_pk_mul_f32 v[168:169], v[172:173], v[168:169]
	s_nop 1
	v_mov_b32_dpp v172, v170 row_ror:8 row_mask:0xf bank_mask:0xf
	v_mov_b32_dpp v173, v171 row_ror:8 row_mask:0xf bank_mask:0xf
	v_mov_b32_dpp v174, v168 row_ror:8 row_mask:0xf bank_mask:0xf
	v_mov_b32_dpp v175, v169 row_ror:8 row_mask:0xf bank_mask:0xf
	s_waitcnt lgkmcnt(2)
	v_pk_mul_f32 v[172:173], v[72:73], v[172:173]
	s_nop 0
	v_pk_fma_f32 v[60:61], v[62:63], v[172:173], v[178:179]
	s_waitcnt lgkmcnt(0)
	v_pk_mul_f32 v[172:173], v[72:73], v[174:175]
	v_pk_mul_f32 v[174:175], v[176:177], v[168:169]
	v_cndmask_b32_e64 v61, v171, v61, s[6:7]
	v_cndmask_b32_e64 v60, v170, v60, s[6:7]
	v_pk_fma_f32 v[62:63], v[62:63], v[172:173], v[174:175]
	v_mul_f32_e32 v60, 0x3e0293ee, v60
	v_mul_f32_e32 v61, 0x3e0293ee, v61
	v_cndmask_b32_e64 v168, v168, v62, s[6:7]
	v_cvt_pk_bf16_f32 v62, v60, v61
	v_lshl_add_u64 v[60:61], v[104:105], 0, s[22:23]
	global_store_dword v[60:61], v62, off
	v_add_co_u32_e32 v62, vcc, s2, v110
	v_cndmask_b32_e64 v169, v169, v63, s[6:7]
	s_nop 0
	v_addc_co_u32_e32 v63, vcc, 0, v111, vcc
	s_waitcnt vmcnt(9)
	v_lshlrev_b32_e32 v110, 16, v167
	v_and_b32_e32 v111, 0xffff0000, v167
	v_and_b32_e32 v167, 0xffff0000, v166
	v_lshlrev_b32_e32 v166, 16, v166
	v_cvt_pk_bf16_f32 v101, v168, v169
	v_pk_add_f32 v[108:109], v[108:109], v[168:169]
	v_pk_mul_f32 v[168:169], v[110:111], v[110:111]
	v_pk_mul_f32 v[170:171], v[166:167], v[166:167]
	v_mov_b32_e32 v173, v168
	v_mov_b32_e32 v172, v170
	v_mov_b32_e32 v168, v171
	v_pk_add_f32 v[168:169], v[172:173], v[168:169]
	s_nop 1
	v_mov_b32_dpp v171, v169 quad_perm:[1,0,3,2] row_mask:0xf bank_mask:0xf
	v_mov_b32_dpp v170, v168 quad_perm:[1,0,3,2] row_mask:0xf bank_mask:0xf
	global_store_dword v[62:63], v101, off
	v_mov_b32_e32 v172, v56
	v_mov_b32_e32 v173, v58
	v_mov_b32_e32 v58, v57
	s_waitcnt lgkmcnt(0)
	v_pk_add_f32 v[168:169], v[168:169], v[170:171]
	s_nop 1
	v_mov_b32_dpp v171, v169 quad_perm:[2,3,0,1] row_mask:0xf bank_mask:0xf
	v_mov_b32_dpp v170, v168 quad_perm:[2,3,0,1] row_mask:0xf bank_mask:0xf
	s_add_u32 s22, s22, 0x800
	s_addc_u32 s23, s23, 0
	s_cmpk_eq_i32 s22, 0x2000
	s_waitcnt lgkmcnt(0)
	v_pk_add_f32 v[168:169], v[168:169], v[170:171]
	s_nop 1
	v_mov_b32_dpp v171, v169 row_half_mirror row_mask:0xf bank_mask:0xf
	v_mov_b32_dpp v170, v168 row_half_mirror row_mask:0xf bank_mask:0xf
	s_waitcnt lgkmcnt(0)
	v_pk_add_f32 v[168:169], v[168:169], v[170:171]
	s_nop 1
	v_mov_b32_dpp v171, v169 row_ror:8 row_mask:0xf bank_mask:0xf
	v_mov_b32_dpp v170, v168 row_ror:8 row_mask:0xf bank_mask:0xf
	s_waitcnt lgkmcnt(0)
	v_pk_add_f32 v[168:169], v[168:169], v[170:171]
	s_waitcnt lgkmcnt(0)
	v_mov_b32_e32 v171, v169
	v_mov_b32_e32 v170, v168
	s_nop 1
	v_permlane16_swap_b32_e32 v169, v171
	v_permlane16_swap_b32_e32 v168, v170
	s_nop 0
	v_pk_add_f32 v[168:169], v[168:169], v[170:171]
	s_waitcnt lgkmcnt(0)
	v_mov_b32_e32 v171, v169
	v_mov_b32_e32 v170, v168
	s_nop 1
	v_permlane32_swap_b32_e32 v169, v171
	v_permlane32_swap_b32_e32 v168, v170
	s_nop 0
	v_pk_add_f32 v[168:169], v[168:169], v[170:171]
	s_nop 0
	v_pk_fma_f32 v[168:169], v[168:169], s[64:65], v[106:107] op_sel_hi:[1,0,0]
	s_nop 0
	v_mul_f32_e32 v101, 0x4b800000, v169
	v_cmp_gt_f32_e64 s[10:11], s40, v169
	v_cmp_gt_f32_e32 vcc, s40, v168
	s_nop 0
	v_cndmask_b32_e64 v101, v169, v101, s[10:11]
	v_rsq_f32_e32 v101, v101
	s_nop 0
	v_mul_f32_e32 v169, 0x45800000, v101
	v_cndmask_b32_e64 v170, v101, v169, s[10:11]
	v_mul_f32_e32 v101, 0x4b800000, v168
	v_cndmask_b32_e32 v101, v168, v101, vcc
	v_rsq_f32_e32 v101, v101
	s_nop 0
	v_mul_f32_e32 v168, 0x45800000, v101
	v_cndmask_b32_e32 v168, v101, v168, vcc
	v_pk_mul_f32 v[168:169], v[64:65], v[168:169] op_sel_hi:[1,0]
	s_nop 0
	v_pk_mul_f32 v[166:167], v[168:169], v[166:167]
	v_pk_mul_f32 v[168:169], v[66:67], v[170:171] op_sel_hi:[1,0]
	v_pk_mul_f32 v[174:175], v[172:173], v[166:167]
	v_pk_mul_f32 v[110:111], v[168:169], v[110:111]
	s_nop 1
	v_mov_b32_dpp v168, v166 row_ror:8 row_mask:0xf bank_mask:0xf
	v_mov_b32_dpp v169, v167 row_ror:8 row_mask:0xf bank_mask:0xf
	v_mov_b32_dpp v170, v110 row_ror:8 row_mask:0xf bank_mask:0xf
	v_mov_b32_dpp v171, v111 row_ror:8 row_mask:0xf bank_mask:0xf
	s_waitcnt lgkmcnt(2)
	v_pk_mul_f32 v[168:169], v[72:73], v[168:169]
	s_nop 0
	v_pk_fma_f32 v[56:57], v[58:59], v[168:169], v[174:175]
	v_pk_mul_f32 v[168:169], v[172:173], v[110:111]
	v_cndmask_b32_e64 v56, v166, v56, s[6:7]
	s_waitcnt lgkmcnt(0)
	v_pk_mul_f32 v[170:171], v[72:73], v[170:171]
	v_cndmask_b32_e64 v57, v167, v57, s[6:7]
	v_mul_f32_e32 v56, 0x3e0293ee, v56
	v_pk_fma_f32 v[58:59], v[58:59], v[170:171], v[168:169]
	v_mul_f32_e32 v57, 0x3e0293ee, v57
	v_cvt_pk_bf16_f32 v56, v56, v57
	v_cndmask_b32_e64 v59, v111, v59, s[6:7]
	v_cndmask_b32_e64 v58, v110, v58, s[6:7]
	global_store_dword v[60:61], v56, off offset:256
	v_cvt_pk_bf16_f32 v56, v58, v59
	global_store_dword v[62:63], v56, off offset:256
	v_pk_add_f32 v[56:57], v[108:109], v[58:59]
	s_waitcnt vmcnt(11)
	v_lshlrev_b32_e32 v58, 16, v165
	v_and_b32_e32 v59, 0xffff0000, v165
	v_and_b32_e32 v109, 0xffff0000, v158
	v_lshlrev_b32_e32 v108, 16, v158
	v_pk_mul_f32 v[110:111], v[108:109], v[108:109]
	v_pk_mul_f32 v[166:167], v[58:59], v[58:59]
	v_mov_b32_e32 v169, v110
	v_mov_b32_e32 v168, v166
	v_mov_b32_e32 v110, v167
	v_pk_add_f32 v[110:111], v[168:169], v[110:111]
	s_nop 1
	v_mov_b32_dpp v167, v111 quad_perm:[1,0,3,2] row_mask:0xf bank_mask:0xf
	v_mov_b32_dpp v166, v110 quad_perm:[1,0,3,2] row_mask:0xf bank_mask:0xf
	v_mov_b32_e32 v168, v52
	v_mov_b32_e32 v169, v54
	v_mov_b32_e32 v54, v53
	s_waitcnt lgkmcnt(0)
	v_pk_add_f32 v[110:111], v[110:111], v[166:167]
	s_nop 1
	v_mov_b32_dpp v167, v111 quad_perm:[2,3,0,1] row_mask:0xf bank_mask:0xf
	v_mov_b32_dpp v166, v110 quad_perm:[2,3,0,1] row_mask:0xf bank_mask:0xf
	s_waitcnt lgkmcnt(0)
	v_pk_add_f32 v[110:111], v[110:111], v[166:167]
	s_nop 1
	v_mov_b32_dpp v167, v111 row_half_mirror row_mask:0xf bank_mask:0xf
	v_mov_b32_dpp v166, v110 row_half_mirror row_mask:0xf bank_mask:0xf
	s_waitcnt lgkmcnt(0)
	v_pk_add_f32 v[110:111], v[110:111], v[166:167]
	s_nop 1
	v_mov_b32_dpp v167, v111 row_ror:8 row_mask:0xf bank_mask:0xf
	v_mov_b32_dpp v166, v110 row_ror:8 row_mask:0xf bank_mask:0xf
	s_waitcnt lgkmcnt(0)
	v_pk_add_f32 v[110:111], v[110:111], v[166:167]
	s_waitcnt lgkmcnt(0)
	v_mov_b32_e32 v167, v111
	v_mov_b32_e32 v166, v110
	s_nop 1
	v_permlane16_swap_b32_e32 v111, v167
	v_permlane16_swap_b32_e32 v110, v166
	s_nop 0
	v_pk_add_f32 v[110:111], v[110:111], v[166:167]
	s_waitcnt lgkmcnt(0)
	v_mov_b32_e32 v167, v111
	v_mov_b32_e32 v166, v110
	s_nop 1
	v_permlane32_swap_b32_e32 v111, v167
	v_permlane32_swap_b32_e32 v110, v166
	s_nop 0
	v_pk_add_f32 v[110:111], v[110:111], v[166:167]
	s_nop 0
	v_pk_fma_f32 v[110:111], v[110:111], s[64:65], v[106:107] op_sel_hi:[1,0,0]
	s_nop 0
	v_mul_f32_e32 v101, 0x4b800000, v111
	v_cmp_gt_f32_e64 s[10:11], s40, v111
	v_cmp_gt_f32_e32 vcc, s40, v110
	s_nop 0
	v_cndmask_b32_e64 v101, v111, v101, s[10:11]
	v_rsq_f32_e32 v101, v101
	s_nop 0
	v_mul_f32_e32 v111, 0x45800000, v101
	v_cndmask_b32_e64 v158, v101, v111, s[10:11]
	v_mul_f32_e32 v101, 0x4b800000, v110
	v_cndmask_b32_e32 v101, v110, v101, vcc
	v_rsq_f32_e32 v101, v101
	v_pk_mul_f32 v[166:167], v[64:65], v[158:159] op_sel_hi:[1,0]
	v_mul_f32_e32 v110, 0x45800000, v101
	v_cndmask_b32_e32 v110, v101, v110, vcc
	v_pk_mul_f32 v[108:109], v[166:167], v[108:109]
	v_pk_mul_f32 v[110:111], v[66:67], v[110:111] op_sel_hi:[1,0]
	v_pk_mul_f32 v[170:171], v[168:169], v[108:109]
	v_pk_mul_f32 v[58:59], v[110:111], v[58:59]
	s_nop 1
	v_mov_b32_dpp v110, v108 row_ror:8 row_mask:0xf bank_mask:0xf
	v_mov_b32_dpp v111, v109 row_ror:8 row_mask:0xf bank_mask:0xf
	v_mov_b32_dpp v166, v58 row_ror:8 row_mask:0xf bank_mask:0xf
	v_mov_b32_dpp v167, v59 row_ror:8 row_mask:0xf bank_mask:0xf
	s_waitcnt lgkmcnt(2)
	v_pk_mul_f32 v[110:111], v[72:73], v[110:111]
	s_nop 0
	v_pk_fma_f32 v[52:53], v[54:55], v[110:111], v[170:171]
	v_pk_mul_f32 v[110:111], v[168:169], v[58:59]
	v_cndmask_b32_e64 v52, v108, v52, s[6:7]
	s_waitcnt lgkmcnt(0)
	v_pk_mul_f32 v[166:167], v[72:73], v[166:167]
	v_cndmask_b32_e64 v53, v109, v53, s[6:7]
	v_mul_f32_e32 v52, 0x3e0293ee, v52
	v_pk_fma_f32 v[54:55], v[54:55], v[166:167], v[110:111]
	v_mul_f32_e32 v53, 0x3e0293ee, v53
	v_cvt_pk_bf16_f32 v52, v52, v53
	v_cndmask_b32_e64 v55, v59, v55, s[6:7]
	v_cndmask_b32_e64 v54, v58, v54, s[6:7]
	global_store_dword v[60:61], v52, off offset:512
	v_cvt_pk_bf16_f32 v52, v54, v55
	global_store_dword v[62:63], v52, off offset:512
	v_pk_add_f32 v[52:53], v[56:57], v[54:55]
	s_waitcnt vmcnt(12)
	v_lshlrev_b32_e32 v54, 16, v155
	v_and_b32_e32 v55, 0xffff0000, v155
	v_and_b32_e32 v57, 0xffff0000, v154
	v_lshlrev_b32_e32 v56, 16, v154
	v_pk_mul_f32 v[58:59], v[56:57], v[56:57]
	v_pk_mul_f32 v[108:109], v[54:55], v[54:55]
	v_mov_b32_e32 v111, v58
	v_mov_b32_e32 v110, v108
	v_mov_b32_e32 v58, v109
	v_pk_add_f32 v[58:59], v[110:111], v[58:59]
	s_nop 1
	v_mov_b32_dpp v109, v59 quad_perm:[1,0,3,2] row_mask:0xf bank_mask:0xf
	v_mov_b32_dpp v108, v58 quad_perm:[1,0,3,2] row_mask:0xf bank_mask:0xf
	v_mov_b32_e32 v110, v48
	v_mov_b32_e32 v111, v50
	v_mov_b32_e32 v50, v49
	s_waitcnt lgkmcnt(0)
	v_pk_add_f32 v[58:59], v[58:59], v[108:109]
	s_nop 1
	v_mov_b32_dpp v109, v59 quad_perm:[2,3,0,1] row_mask:0xf bank_mask:0xf
	v_mov_b32_dpp v108, v58 quad_perm:[2,3,0,1] row_mask:0xf bank_mask:0xf
	s_waitcnt lgkmcnt(0)
	v_pk_add_f32 v[58:59], v[58:59], v[108:109]
	s_nop 1
	v_mov_b32_dpp v109, v59 row_half_mirror row_mask:0xf bank_mask:0xf
	v_mov_b32_dpp v108, v58 row_half_mirror row_mask:0xf bank_mask:0xf
	s_waitcnt lgkmcnt(0)
	v_pk_add_f32 v[58:59], v[58:59], v[108:109]
	s_nop 1
	v_mov_b32_dpp v109, v59 row_ror:8 row_mask:0xf bank_mask:0xf
	v_mov_b32_dpp v108, v58 row_ror:8 row_mask:0xf bank_mask:0xf
	s_waitcnt lgkmcnt(0)
	v_pk_add_f32 v[58:59], v[58:59], v[108:109]
	s_waitcnt lgkmcnt(0)
	v_mov_b32_e32 v109, v59
	v_mov_b32_e32 v108, v58
	s_nop 1
	v_permlane16_swap_b32_e32 v59, v109
	v_permlane16_swap_b32_e32 v58, v108
	s_nop 0
	v_pk_add_f32 v[58:59], v[58:59], v[108:109]
	s_waitcnt lgkmcnt(0)
	v_mov_b32_e32 v109, v59
	v_mov_b32_e32 v108, v58
	s_nop 1
	v_permlane32_swap_b32_e32 v59, v109
	v_permlane32_swap_b32_e32 v58, v108
	s_nop 0
	v_pk_add_f32 v[58:59], v[58:59], v[108:109]
	s_nop 0
	v_pk_fma_f32 v[58:59], v[58:59], s[64:65], v[106:107] op_sel_hi:[1,0,0]
	s_nop 0
	v_mul_f32_e32 v101, 0x4b800000, v59
	v_cmp_gt_f32_e64 s[10:11], s40, v59
	v_cmp_gt_f32_e32 vcc, s40, v58
	s_nop 0
	v_cndmask_b32_e64 v59, v59, v101, s[10:11]
	v_rsq_f32_e32 v59, v59
	s_nop 0
	v_mul_f32_e32 v101, 0x45800000, v59
	v_cndmask_b32_e64 v108, v59, v101, s[10:11]
	v_mul_f32_e32 v59, 0x4b800000, v58
	v_cndmask_b32_e32 v58, v58, v59, vcc
	v_rsq_f32_e32 v58, v58
	v_pk_mul_f32 v[108:109], v[64:65], v[108:109] op_sel_hi:[1,0]
	v_mul_f32_e32 v59, 0x45800000, v58
	v_cndmask_b32_e32 v58, v58, v59, vcc
	v_pk_mul_f32 v[56:57], v[108:109], v[56:57]
	v_pk_mul_f32 v[58:59], v[66:67], v[58:59] op_sel_hi:[1,0]
	v_pk_mul_f32 v[154:155], v[110:111], v[56:57]
	v_pk_mul_f32 v[54:55], v[58:59], v[54:55]
	s_nop 1
	v_mov_b32_dpp v58, v56 row_ror:8 row_mask:0xf bank_mask:0xf
	v_mov_b32_dpp v59, v57 row_ror:8 row_mask:0xf bank_mask:0xf
	v_mov_b32_dpp v108, v54 row_ror:8 row_mask:0xf bank_mask:0xf
	v_mov_b32_dpp v109, v55 row_ror:8 row_mask:0xf bank_mask:0xf
	s_waitcnt lgkmcnt(2)
	v_pk_mul_f32 v[58:59], v[72:73], v[58:59]
	s_nop 0
	v_pk_fma_f32 v[48:49], v[50:51], v[58:59], v[154:155]
	v_pk_mul_f32 v[58:59], v[110:111], v[54:55]
	v_cndmask_b32_e64 v48, v56, v48, s[6:7]
	s_waitcnt lgkmcnt(0)
	v_pk_mul_f32 v[108:109], v[72:73], v[108:109]
	v_cndmask_b32_e64 v49, v57, v49, s[6:7]
	v_mul_f32_e32 v48, 0x3e0293ee, v48
	v_pk_fma_f32 v[50:51], v[50:51], v[108:109], v[58:59]
	v_mul_f32_e32 v49, 0x3e0293ee, v49
	v_cvt_pk_bf16_f32 v48, v48, v49
	v_cndmask_b32_e64 v51, v55, v51, s[6:7]
	v_cndmask_b32_e64 v50, v54, v50, s[6:7]
	global_store_dword v[60:61], v48, off offset:768
	v_cvt_pk_bf16_f32 v48, v50, v51
	global_store_dword v[62:63], v48, off offset:768
	v_pk_add_f32 v[48:49], v[52:53], v[50:51]
	v_and_b32_e32 v51, 0xffff0000, v152
	v_lshlrev_b32_e32 v50, 16, v152
	s_waitcnt vmcnt(13)
	v_lshlrev_b32_e32 v54, 16, v153
	v_and_b32_e32 v55, 0xffff0000, v153
	v_pk_mul_f32 v[52:53], v[50:51], v[50:51]
	v_pk_mul_f32 v[56:57], v[54:55], v[54:55]
	v_mov_b32_e32 v59, v52
	v_mov_b32_e32 v58, v56
	v_mov_b32_e32 v52, v57
	v_pk_add_f32 v[52:53], v[58:59], v[52:53]
	s_nop 1
	v_mov_b32_dpp v57, v53 quad_perm:[1,0,3,2] row_mask:0xf bank_mask:0xf
	v_mov_b32_dpp v56, v52 quad_perm:[1,0,3,2] row_mask:0xf bank_mask:0xf
	v_mov_b32_e32 v58, v44
	v_mov_b32_e32 v59, v46
	v_mov_b32_e32 v46, v45
	s_waitcnt lgkmcnt(0)
	v_pk_add_f32 v[52:53], v[52:53], v[56:57]
	s_nop 1
	v_mov_b32_dpp v57, v53 quad_perm:[2,3,0,1] row_mask:0xf bank_mask:0xf
	v_mov_b32_dpp v56, v52 quad_perm:[2,3,0,1] row_mask:0xf bank_mask:0xf
	s_waitcnt lgkmcnt(0)
	v_pk_add_f32 v[52:53], v[52:53], v[56:57]
	s_nop 1
	v_mov_b32_dpp v57, v53 row_half_mirror row_mask:0xf bank_mask:0xf
	v_mov_b32_dpp v56, v52 row_half_mirror row_mask:0xf bank_mask:0xf
	s_waitcnt lgkmcnt(0)
	v_pk_add_f32 v[52:53], v[52:53], v[56:57]
	s_nop 1
	v_mov_b32_dpp v57, v53 row_ror:8 row_mask:0xf bank_mask:0xf
	v_mov_b32_dpp v56, v52 row_ror:8 row_mask:0xf bank_mask:0xf
	s_waitcnt lgkmcnt(0)
	v_pk_add_f32 v[52:53], v[52:53], v[56:57]
	s_waitcnt lgkmcnt(0)
	v_mov_b32_e32 v57, v53
	v_mov_b32_e32 v56, v52
	s_nop 1
	v_permlane16_swap_b32_e32 v53, v57
	v_permlane16_swap_b32_e32 v52, v56
	s_nop 0
	v_pk_add_f32 v[52:53], v[52:53], v[56:57]
	s_waitcnt lgkmcnt(0)
	v_mov_b32_e32 v57, v53
	v_mov_b32_e32 v56, v52
	s_nop 1
	v_permlane32_swap_b32_e32 v53, v57
	v_permlane32_swap_b32_e32 v52, v56
	s_nop 0
	v_pk_add_f32 v[52:53], v[52:53], v[56:57]
	s_nop 0
	v_pk_fma_f32 v[52:53], v[52:53], s[64:65], v[106:107] op_sel_hi:[1,0,0]
	s_nop 0
	v_mul_f32_e32 v56, 0x4b800000, v53
	v_cmp_gt_f32_e64 s[10:11], s40, v53
	v_cmp_gt_f32_e32 vcc, s40, v52
	s_nop 0
	v_cndmask_b32_e64 v53, v53, v56, s[10:11]
	v_rsq_f32_e32 v53, v53
	s_nop 0
	v_mul_f32_e32 v56, 0x45800000, v53
	v_cndmask_b32_e64 v56, v53, v56, s[10:11]
	v_mul_f32_e32 v53, 0x4b800000, v52
	v_cndmask_b32_e32 v52, v52, v53, vcc
	v_rsq_f32_e32 v52, v52
	v_pk_mul_f32 v[56:57], v[64:65], v[56:57] op_sel_hi:[1,0]
	v_mul_f32_e32 v53, 0x45800000, v52
	v_cndmask_b32_e32 v52, v52, v53, vcc
	v_pk_mul_f32 v[50:51], v[56:57], v[50:51]
	v_pk_mul_f32 v[52:53], v[66:67], v[52:53] op_sel_hi:[1,0]
	v_pk_mul_f32 v[108:109], v[58:59], v[50:51]
	v_pk_mul_f32 v[52:53], v[52:53], v[54:55]
	s_nop 1
	v_mov_b32_dpp v54, v50 row_ror:8 row_mask:0xf bank_mask:0xf
	v_mov_b32_dpp v55, v51 row_ror:8 row_mask:0xf bank_mask:0xf
	v_mov_b32_dpp v56, v52 row_ror:8 row_mask:0xf bank_mask:0xf
	v_mov_b32_dpp v57, v53 row_ror:8 row_mask:0xf bank_mask:0xf
	s_waitcnt lgkmcnt(2)
	v_pk_mul_f32 v[54:55], v[72:73], v[54:55]
	s_nop 0
	v_pk_fma_f32 v[44:45], v[46:47], v[54:55], v[108:109]
	v_pk_mul_f32 v[54:55], v[58:59], v[52:53]
	v_cndmask_b32_e64 v44, v50, v44, s[6:7]
	s_waitcnt lgkmcnt(0)
	v_pk_mul_f32 v[56:57], v[72:73], v[56:57]
	v_cndmask_b32_e64 v45, v51, v45, s[6:7]
	v_mul_f32_e32 v44, 0x3e0293ee, v44
	v_pk_fma_f32 v[46:47], v[46:47], v[56:57], v[54:55]
	v_mul_f32_e32 v45, 0x3e0293ee, v45
	v_cvt_pk_bf16_f32 v44, v44, v45
	v_cndmask_b32_e64 v47, v53, v47, s[6:7]
	v_cndmask_b32_e64 v46, v52, v46, s[6:7]
	global_store_dword v[60:61], v44, off offset:1024
	v_cvt_pk_bf16_f32 v44, v46, v47
	global_store_dword v[62:63], v44, off offset:1024
	v_pk_add_f32 v[44:45], v[48:49], v[46:47]
	v_and_b32_e32 v47, 0xffff0000, v150
	v_lshlrev_b32_e32 v46, 16, v150
	s_waitcnt vmcnt(14)
	v_lshlrev_b32_e32 v50, 16, v151
	v_and_b32_e32 v51, 0xffff0000, v151
	v_pk_mul_f32 v[48:49], v[46:47], v[46:47]
	v_pk_mul_f32 v[52:53], v[50:51], v[50:51]
	v_mov_b32_e32 v55, v48
	v_mov_b32_e32 v54, v52
	v_mov_b32_e32 v48, v53
	v_pk_add_f32 v[48:49], v[54:55], v[48:49]
	s_nop 1
	v_mov_b32_dpp v53, v49 quad_perm:[1,0,3,2] row_mask:0xf bank_mask:0xf
	v_mov_b32_dpp v52, v48 quad_perm:[1,0,3,2] row_mask:0xf bank_mask:0xf
	v_mov_b32_e32 v54, v40
	v_mov_b32_e32 v55, v42
	v_mov_b32_e32 v42, v41
	s_waitcnt lgkmcnt(0)
	v_pk_add_f32 v[48:49], v[48:49], v[52:53]
	s_nop 1
	v_mov_b32_dpp v53, v49 quad_perm:[2,3,0,1] row_mask:0xf bank_mask:0xf
	v_mov_b32_dpp v52, v48 quad_perm:[2,3,0,1] row_mask:0xf bank_mask:0xf
	s_waitcnt lgkmcnt(0)
	v_pk_add_f32 v[48:49], v[48:49], v[52:53]
	s_nop 1
	v_mov_b32_dpp v53, v49 row_half_mirror row_mask:0xf bank_mask:0xf
	v_mov_b32_dpp v52, v48 row_half_mirror row_mask:0xf bank_mask:0xf
	s_waitcnt lgkmcnt(0)
	v_pk_add_f32 v[48:49], v[48:49], v[52:53]
	s_nop 1
	v_mov_b32_dpp v53, v49 row_ror:8 row_mask:0xf bank_mask:0xf
	v_mov_b32_dpp v52, v48 row_ror:8 row_mask:0xf bank_mask:0xf
	s_waitcnt lgkmcnt(0)
	v_pk_add_f32 v[48:49], v[48:49], v[52:53]
	s_waitcnt lgkmcnt(0)
	v_mov_b32_e32 v53, v49
	v_mov_b32_e32 v52, v48
	s_nop 1
	v_permlane16_swap_b32_e32 v49, v53
	v_permlane16_swap_b32_e32 v48, v52
	s_nop 0
	v_pk_add_f32 v[48:49], v[48:49], v[52:53]
	s_waitcnt lgkmcnt(0)
	v_mov_b32_e32 v53, v49
	v_mov_b32_e32 v52, v48
	s_nop 1
	v_permlane32_swap_b32_e32 v49, v53
	v_permlane32_swap_b32_e32 v48, v52
	s_nop 0
	v_pk_add_f32 v[48:49], v[48:49], v[52:53]
	s_nop 0
	v_pk_fma_f32 v[48:49], v[48:49], s[64:65], v[106:107] op_sel_hi:[1,0,0]
	s_nop 0
	v_mul_f32_e32 v52, 0x4b800000, v49
	v_cmp_gt_f32_e64 s[10:11], s40, v49
	v_cmp_gt_f32_e32 vcc, s40, v48
	s_nop 0
	v_cndmask_b32_e64 v49, v49, v52, s[10:11]
	v_rsq_f32_e32 v49, v49
	s_nop 0
	v_mul_f32_e32 v52, 0x45800000, v49
	v_cndmask_b32_e64 v52, v49, v52, s[10:11]
	v_mul_f32_e32 v49, 0x4b800000, v48
	v_cndmask_b32_e32 v48, v48, v49, vcc
	v_rsq_f32_e32 v48, v48
	v_pk_mul_f32 v[52:53], v[64:65], v[52:53] op_sel_hi:[1,0]
	v_mul_f32_e32 v49, 0x45800000, v48
	v_cndmask_b32_e32 v48, v48, v49, vcc
	v_pk_mul_f32 v[46:47], v[52:53], v[46:47]
	v_pk_mul_f32 v[48:49], v[66:67], v[48:49] op_sel_hi:[1,0]
	v_pk_mul_f32 v[56:57], v[54:55], v[46:47]
	v_pk_mul_f32 v[48:49], v[48:49], v[50:51]
	s_nop 1
	v_mov_b32_dpp v50, v46 row_ror:8 row_mask:0xf bank_mask:0xf
	v_mov_b32_dpp v51, v47 row_ror:8 row_mask:0xf bank_mask:0xf
	v_mov_b32_dpp v52, v48 row_ror:8 row_mask:0xf bank_mask:0xf
	v_mov_b32_dpp v53, v49 row_ror:8 row_mask:0xf bank_mask:0xf
	s_waitcnt lgkmcnt(2)
	v_pk_mul_f32 v[50:51], v[72:73], v[50:51]
	s_nop 0
	v_pk_fma_f32 v[40:41], v[42:43], v[50:51], v[56:57]
	v_pk_mul_f32 v[50:51], v[54:55], v[48:49]
	v_cndmask_b32_e64 v40, v46, v40, s[6:7]
	s_waitcnt lgkmcnt(0)
	v_pk_mul_f32 v[52:53], v[72:73], v[52:53]
	v_cndmask_b32_e64 v41, v47, v41, s[6:7]
	v_mul_f32_e32 v40, 0x3e0293ee, v40
	v_pk_fma_f32 v[42:43], v[42:43], v[52:53], v[50:51]
	v_mul_f32_e32 v41, 0x3e0293ee, v41
	v_cvt_pk_bf16_f32 v40, v40, v41
	v_cndmask_b32_e64 v43, v49, v43, s[6:7]
	v_cndmask_b32_e64 v42, v48, v42, s[6:7]
	global_store_dword v[60:61], v40, off offset:1280
	v_cvt_pk_bf16_f32 v40, v42, v43
	global_store_dword v[62:63], v40, off offset:1280
	v_pk_add_f32 v[40:41], v[44:45], v[42:43]
	v_and_b32_e32 v43, 0xffff0000, v148
	v_lshlrev_b32_e32 v42, 16, v148
	s_waitcnt vmcnt(15)
	v_lshlrev_b32_e32 v46, 16, v149
	v_and_b32_e32 v47, 0xffff0000, v149
	v_pk_mul_f32 v[44:45], v[42:43], v[42:43]
	v_pk_mul_f32 v[48:49], v[46:47], v[46:47]
	v_mov_b32_e32 v51, v44
	v_mov_b32_e32 v50, v48
	v_mov_b32_e32 v44, v49
	v_pk_add_f32 v[44:45], v[50:51], v[44:45]
	s_nop 1
	v_mov_b32_dpp v49, v45 quad_perm:[1,0,3,2] row_mask:0xf bank_mask:0xf
	v_mov_b32_dpp v48, v44 quad_perm:[1,0,3,2] row_mask:0xf bank_mask:0xf
	s_waitcnt vmcnt(13)
	v_mov_b32_e32 v50, v36
	v_mov_b32_e32 v51, v38
	v_mov_b32_e32 v38, v37
	s_waitcnt lgkmcnt(0)
	v_pk_add_f32 v[44:45], v[44:45], v[48:49]
	s_nop 1
	v_mov_b32_dpp v49, v45 quad_perm:[2,3,0,1] row_mask:0xf bank_mask:0xf
	v_mov_b32_dpp v48, v44 quad_perm:[2,3,0,1] row_mask:0xf bank_mask:0xf
	s_waitcnt lgkmcnt(0)
	v_pk_add_f32 v[44:45], v[44:45], v[48:49]
	s_nop 1
	v_mov_b32_dpp v49, v45 row_half_mirror row_mask:0xf bank_mask:0xf
	v_mov_b32_dpp v48, v44 row_half_mirror row_mask:0xf bank_mask:0xf
	s_waitcnt lgkmcnt(0)
	v_pk_add_f32 v[44:45], v[44:45], v[48:49]
	s_nop 1
	v_mov_b32_dpp v49, v45 row_ror:8 row_mask:0xf bank_mask:0xf
	v_mov_b32_dpp v48, v44 row_ror:8 row_mask:0xf bank_mask:0xf
	s_waitcnt lgkmcnt(0)
	v_pk_add_f32 v[44:45], v[44:45], v[48:49]
	s_waitcnt lgkmcnt(0)
	v_mov_b32_e32 v49, v45
	v_mov_b32_e32 v48, v44
	s_nop 1
	v_permlane16_swap_b32_e32 v45, v49
	v_permlane16_swap_b32_e32 v44, v48
	s_nop 0
	v_pk_add_f32 v[44:45], v[44:45], v[48:49]
	s_waitcnt lgkmcnt(0)
	v_mov_b32_e32 v49, v45
	v_mov_b32_e32 v48, v44
	s_nop 1
	v_permlane32_swap_b32_e32 v45, v49
	v_permlane32_swap_b32_e32 v44, v48
	s_nop 0
	v_pk_add_f32 v[44:45], v[44:45], v[48:49]
	s_nop 0
	v_pk_fma_f32 v[44:45], v[44:45], s[64:65], v[106:107] op_sel_hi:[1,0,0]
	s_nop 0
	v_mul_f32_e32 v48, 0x4b800000, v45
	v_cmp_gt_f32_e64 s[10:11], s40, v45
	v_cmp_gt_f32_e32 vcc, s40, v44
	s_nop 0
	v_cndmask_b32_e64 v45, v45, v48, s[10:11]
	v_rsq_f32_e32 v45, v45
	s_nop 0
	v_mul_f32_e32 v48, 0x45800000, v45
	v_cndmask_b32_e64 v48, v45, v48, s[10:11]
	v_mul_f32_e32 v45, 0x4b800000, v44
	v_cndmask_b32_e32 v44, v44, v45, vcc
	v_rsq_f32_e32 v44, v44
	v_pk_mul_f32 v[48:49], v[64:65], v[48:49] op_sel_hi:[1,0]
	v_mul_f32_e32 v45, 0x45800000, v44
	v_cndmask_b32_e32 v44, v44, v45, vcc
	v_pk_mul_f32 v[42:43], v[48:49], v[42:43]
	v_pk_mul_f32 v[44:45], v[66:67], v[44:45] op_sel_hi:[1,0]
	v_pk_mul_f32 v[52:53], v[50:51], v[42:43]
	v_pk_mul_f32 v[44:45], v[44:45], v[46:47]
	s_nop 1
	v_mov_b32_dpp v46, v42 row_ror:8 row_mask:0xf bank_mask:0xf
	v_mov_b32_dpp v47, v43 row_ror:8 row_mask:0xf bank_mask:0xf
	v_mov_b32_dpp v48, v44 row_ror:8 row_mask:0xf bank_mask:0xf
	v_mov_b32_dpp v49, v45 row_ror:8 row_mask:0xf bank_mask:0xf
	s_waitcnt lgkmcnt(2)
	v_pk_mul_f32 v[46:47], v[72:73], v[46:47]
	s_nop 0
	v_pk_fma_f32 v[36:37], v[38:39], v[46:47], v[52:53]
	v_pk_mul_f32 v[46:47], v[50:51], v[44:45]
	v_cndmask_b32_e64 v36, v42, v36, s[6:7]
	s_waitcnt lgkmcnt(0)
	v_pk_mul_f32 v[48:49], v[72:73], v[48:49]
	v_cndmask_b32_e64 v37, v43, v37, s[6:7]
	v_mul_f32_e32 v36, 0x3e0293ee, v36
	v_pk_fma_f32 v[38:39], v[38:39], v[48:49], v[46:47]
	v_mul_f32_e32 v37, 0x3e0293ee, v37
	v_cvt_pk_bf16_f32 v36, v36, v37
	v_cndmask_b32_e64 v39, v45, v39, s[6:7]
	v_cndmask_b32_e64 v38, v44, v38, s[6:7]
	global_store_dword v[60:61], v36, off offset:1536
	v_cvt_pk_bf16_f32 v36, v38, v39
	global_store_dword v[62:63], v36, off offset:1536
	v_pk_add_f32 v[36:37], v[40:41], v[38:39]
	v_and_b32_e32 v39, 0xffff0000, v146
	v_lshlrev_b32_e32 v38, 16, v146
	v_lshlrev_b32_e32 v42, 16, v147
	v_and_b32_e32 v43, 0xffff0000, v147
	v_pk_mul_f32 v[40:41], v[38:39], v[38:39]
	v_pk_mul_f32 v[44:45], v[42:43], v[42:43]
	v_mov_b32_e32 v47, v40
	v_mov_b32_e32 v46, v44
	v_mov_b32_e32 v40, v45
	v_pk_add_f32 v[40:41], v[46:47], v[40:41]
	s_nop 1
	v_mov_b32_dpp v45, v41 quad_perm:[1,0,3,2] row_mask:0xf bank_mask:0xf
	v_mov_b32_dpp v44, v40 quad_perm:[1,0,3,2] row_mask:0xf bank_mask:0xf
	s_waitcnt vmcnt(14)
	v_mov_b32_e32 v46, v32
	v_mov_b32_e32 v47, v34
	v_mov_b32_e32 v34, v33
	s_waitcnt lgkmcnt(0)
	v_pk_add_f32 v[40:41], v[40:41], v[44:45]
	s_nop 1
	v_mov_b32_dpp v45, v41 quad_perm:[2,3,0,1] row_mask:0xf bank_mask:0xf
	v_mov_b32_dpp v44, v40 quad_perm:[2,3,0,1] row_mask:0xf bank_mask:0xf
	s_waitcnt lgkmcnt(0)
	v_pk_add_f32 v[40:41], v[40:41], v[44:45]
	s_nop 1
	v_mov_b32_dpp v45, v41 row_half_mirror row_mask:0xf bank_mask:0xf
	v_mov_b32_dpp v44, v40 row_half_mirror row_mask:0xf bank_mask:0xf
	s_waitcnt lgkmcnt(0)
	v_pk_add_f32 v[40:41], v[40:41], v[44:45]
	s_nop 1
	v_mov_b32_dpp v45, v41 row_ror:8 row_mask:0xf bank_mask:0xf
	v_mov_b32_dpp v44, v40 row_ror:8 row_mask:0xf bank_mask:0xf
	s_waitcnt lgkmcnt(0)
	v_pk_add_f32 v[40:41], v[40:41], v[44:45]
	s_waitcnt lgkmcnt(0)
	v_mov_b32_e32 v45, v41
	v_mov_b32_e32 v44, v40
	s_nop 1
	v_permlane16_swap_b32_e32 v41, v45
	v_permlane16_swap_b32_e32 v40, v44
	s_nop 0
	v_pk_add_f32 v[40:41], v[40:41], v[44:45]
	s_waitcnt lgkmcnt(0)
	v_mov_b32_e32 v45, v41
	v_mov_b32_e32 v44, v40
	s_nop 1
	v_permlane32_swap_b32_e32 v41, v45
	v_permlane32_swap_b32_e32 v40, v44
	s_nop 0
	v_pk_add_f32 v[40:41], v[40:41], v[44:45]
	s_nop 0
	v_pk_fma_f32 v[40:41], v[40:41], s[64:65], v[106:107] op_sel_hi:[1,0,0]
	s_nop 0
	v_mul_f32_e32 v44, 0x4b800000, v41
	v_cmp_gt_f32_e64 s[10:11], s40, v41
	v_cmp_gt_f32_e32 vcc, s40, v40
	s_nop 0
	v_cndmask_b32_e64 v41, v41, v44, s[10:11]
	v_rsq_f32_e32 v41, v41
	s_nop 0
	v_mul_f32_e32 v44, 0x45800000, v41
	v_cndmask_b32_e64 v44, v41, v44, s[10:11]
	v_mul_f32_e32 v41, 0x4b800000, v40
	v_cndmask_b32_e32 v40, v40, v41, vcc
	v_rsq_f32_e32 v40, v40
	v_pk_mul_f32 v[44:45], v[64:65], v[44:45] op_sel_hi:[1,0]
	v_mul_f32_e32 v41, 0x45800000, v40
	v_cndmask_b32_e32 v40, v40, v41, vcc
	v_pk_mul_f32 v[38:39], v[44:45], v[38:39]
	v_pk_mul_f32 v[40:41], v[66:67], v[40:41] op_sel_hi:[1,0]
	v_pk_mul_f32 v[48:49], v[46:47], v[38:39]
	v_pk_mul_f32 v[40:41], v[40:41], v[42:43]
	s_nop 1
	v_mov_b32_dpp v42, v38 row_ror:8 row_mask:0xf bank_mask:0xf
	v_mov_b32_dpp v43, v39 row_ror:8 row_mask:0xf bank_mask:0xf
	v_mov_b32_dpp v44, v40 row_ror:8 row_mask:0xf bank_mask:0xf
	v_mov_b32_dpp v45, v41 row_ror:8 row_mask:0xf bank_mask:0xf
	s_waitcnt lgkmcnt(2)
	v_pk_mul_f32 v[42:43], v[72:73], v[42:43]
	s_nop 0
	v_pk_fma_f32 v[32:33], v[34:35], v[42:43], v[48:49]
	v_pk_mul_f32 v[42:43], v[46:47], v[40:41]
	s_waitcnt lgkmcnt(0)
	v_pk_mul_f32 v[44:45], v[72:73], v[44:45]
	v_cndmask_b32_e64 v32, v38, v32, s[6:7]
	v_pk_fma_f32 v[34:35], v[34:35], v[44:45], v[42:43]
	v_cndmask_b32_e64 v33, v39, v33, s[6:7]
	v_cndmask_b32_e64 v35, v41, v35, s[6:7]
	v_cndmask_b32_e64 v34, v40, v34, s[6:7]
	v_mul_f32_e32 v32, 0x3e0293ee, v32
	v_mul_f32_e32 v33, 0x3e0293ee, v33
	v_cvt_pk_bf16_f32 v32, v32, v33
	v_pk_add_f32 v[108:109], v[36:37], v[34:35]
	global_store_dword v[60:61], v32, off offset:1792
	v_cvt_pk_bf16_f32 v32, v34, v35
	global_store_dword v[62:63], v32, off offset:1792
	s_cbranch_scc0 .LBB0_511
	s_lshl_b64 s[10:11], s[20:21], 8
	s_add_u32 s10, s4, s10
	s_addc_u32 s11, s14, s11
	v_lshl_add_u64 v[32:33], s[10:11], 0, v[74:75]
	global_load_dwordx4 v[214:217], v[32:33], off
	v_lshl_add_u64 v[32:33], s[10:11], 0, v[82:83]
	global_load_dwordx4 v[218:221], v[32:33], off
	v_lshl_add_u64 v[32:33], s[10:11], 0, v[84:85]
	global_load_dwordx4 v[222:225], v[32:33], off
	v_lshl_add_u64 v[32:33], s[10:11], 0, v[86:87]
	global_load_dwordx4 v[226:229], v[32:33], off
	v_lshl_add_u64 v[32:33], s[10:11], 0, v[88:89]
	global_load_dwordx4 v[230:233], v[32:33], off
	v_lshl_add_u64 v[32:33], s[10:11], 0, v[90:91]
	global_load_dwordx4 v[234:237], v[32:33], off
	v_lshl_add_u64 v[32:33], s[10:11], 0, v[92:93]
	global_load_dwordx4 v[238:241], v[32:33], off
	v_lshl_add_u64 v[32:33], s[10:11], 0, v[94:95]
	global_load_dwordx4 v[242:245], v[32:33], off
	s_barrier
	ds_write_b64 v120, v[108:109]
	s_waitcnt vmcnt(7)
	ds_write_b128 v121, v[214:217]
	s_waitcnt vmcnt(6)
	ds_write_b128 v122, v[218:221]
	s_waitcnt vmcnt(5)
	ds_write_b128 v123, v[222:225]
	s_waitcnt vmcnt(4)
	ds_write_b128 v124, v[226:229]
	s_waitcnt vmcnt(3)
	ds_write_b128 v125, v[230:233]
	s_waitcnt vmcnt(2)
	ds_write_b128 v126, v[234:237]
	s_waitcnt vmcnt(1)
	ds_write_b128 v127, v[238:241]
	s_waitcnt vmcnt(0)
	ds_write_b128 v128, v[242:245]
	s_waitcnt lgkmcnt(0)
	s_barrier
	s_and_saveexec_b64 s[10:11], s[8:9]
	s_xor_b64 s[10:11], exec, s[10:11]
	s_lshl_b32 s2, s31, 6
	s_add_i32 s20, s2, s25
	s_ashr_i32 s21, s20, 31
	s_or_saveexec_b64 s[10:11], s[10:11]
	v_mov_b64_e32 v[32:33], s[20:21]
	s_xor_b64 exec, exec, s[10:11]
	s_cbranch_execz .LBB0_509
	ds_read2st64_b32 v[32:33], v119 offset1:2
	s_lshl_b32 s2, s31, 6
	s_add_i32 s20, s2, s25
	s_ashr_i32 s21, s20, 31
	s_lshl_b64 s[22:23], s[20:21], 9
	s_waitcnt lgkmcnt(0)
	v_add_f32_e32 v32, 0, v32
	v_add_f32_e32 v34, v32, v33
	ds_read2st64_b32 v[32:33], v119 offset0:4 offset1:6
	s_waitcnt lgkmcnt(0)
	v_add_f32_e32 v32, v34, v32
	v_add_f32_e32 v34, v32, v33
	ds_read2st64_b32 v[32:33], v119 offset0:8 offset1:10
	s_waitcnt lgkmcnt(0)
	v_add_f32_e32 v32, v34, v32
	v_add_f32_e32 v34, v32, v33
	ds_read2st64_b32 v[32:33], v119 offset0:12 offset1:14
	s_waitcnt lgkmcnt(0)
	v_add_f32_e32 v32, v34, v32
	v_add_f32_e32 v32, v32, v33
	v_mul_f32_e32 v34, 0x3b800000, v32
	v_lshl_add_u64 v[32:33], v[76:77], 0, s[22:23]
	global_store_dword v[32:33], v34, off
	v_mov_b64_e32 v[32:33], s[20:21]
	s_branch .LBB0_509
